# R3->ff1a grid barrier split: arrive after each wave's context rows inside R3, wait+acquire before ff1a
# speedup vs baseline: 1.0059x; 1.0034x over previous
.LBB0_630:
	s_cmp_lt_i32 s96, 8
	s_cselect_b64 s[4:5], -1, 0
	s_and_b64 s[4:5], s[4:5], s[0:1]
	s_andn2_b64 vcc, exec, s[4:5]
	s_cbranch_vccnz .LBB0_638
	s_cmpk_gt_i32 s44, 0x1fff
	s_cbranch_scc1 .LBB0_638
	s_mov_b32 s45, 0
	v_mbcnt_lo_u32_b32 v1, -1, 0
	s_waitcnt lgkmcnt(0)
	v_mbcnt_hi_u32_b32 v3, -1, v1
	v_and_b32_e32 v1, 64, v3
	v_add_u32_e32 v5, 64, v1
	v_xor_b32_e32 v1, 1, v3
	v_cmp_lt_i32_e32 vcc, v1, v5
	v_xor_b32_e32 v7, 2, v3
	v_readlane_b32 s0, v254, 2
	v_cndmask_b32_e32 v1, v3, v1, vcc
	v_cmp_lt_i32_e32 vcc, v7, v5
	v_readlane_b32 s1, v254, 3
	v_lshlrev_b32_e32 v2, 3, v191
	v_cndmask_b32_e32 v7, v3, v7, vcc
	v_lshlrev_b32_e32 v157, 2, v7
	v_xor_b32_e32 v7, 4, v3
	v_cmp_lt_i32_e32 vcc, v7, v5
	v_readlane_b32 s0, v254, 4
	v_mov_b32_e32 v83, 0
	v_cndmask_b32_e32 v7, v3, v7, vcc
	v_or_b32_e32 v6, 0x400, v2
	v_lshlrev_b32_e32 v158, 2, v7
	v_xor_b32_e32 v7, 8, v3
	v_readlane_b32 s1, v254, 5
	v_lshlrev_b32_e32 v82, 5, v191
	v_lshlrev_b32_e32 v10, 2, v6
	v_mov_b32_e32 v11, v83
	v_cmp_lt_i32_e32 vcc, v7, v5
	v_lshl_add_u64 v[86:87], s[50:51], 0, v[10:11]
	v_lshl_add_u64 v[92:93], s[52:53], 0, v[10:11]
	v_lshl_add_u64 v[10:11], s[62:63], 0, v[82:83]
	s_mov_b64 s[0:1], 0x80000
	v_cndmask_b32_e32 v7, v3, v7, vcc
	v_lshl_add_u64 v[96:97], v[10:11], 0, s[0:1]
	s_lshl_b32 s6, s44, 1
	v_lshlrev_b32_e32 v159, 2, v7
	v_xor_b32_e32 v7, 16, v3
	s_lshl_b32 s0, s2, 8
	s_lshl_b32 s1, s89, 5
	v_cmp_lt_i32_e32 vcc, v7, v5
	s_add_i32 s3, s0, s1
	s_lshl_b32 s0, s2, 14
	s_lshl_b32 s1, s89, 11
	s_ashr_i32 s7, s6, 31
	v_cndmask_b32_e32 v7, v3, v7, vcc
	s_lshl_b32 s25, s33, 8
	s_add_i32 s27, s0, s1
	s_lshl_b32 s28, s33, 14
	s_ashr_i32 s49, s48, 31
	s_lshl_b64 s[0:1], s[6:7], 12
	v_lshlrev_b32_e32 v160, 2, v7
	v_xor_b32_e32 v7, 32, v3
	s_add_u32 s0, s62, s0
	v_or_b32_e32 v8, 0x600, v2
	v_lshl_add_u64 v[84:85], s[50:51], 0, v[82:83]
	v_lshl_add_u64 v[90:91], s[52:53], 0, v[82:83]
	v_cmp_lt_i32_e32 vcc, v7, v5
	v_lshlrev_b32_e32 v82, 4, v191
	s_addc_u32 s1, s63, s1
	v_or_b32_e32 v4, 0x200, v2
	v_lshlrev_b32_e32 v12, 2, v8
	v_mov_b32_e32 v13, v83
	v_cndmask_b32_e32 v3, v3, v7, vcc
	v_lshl_add_u64 v[10:11], s[0:1], 0, v[82:83]
	s_mov_b64 s[0:1], 0x14800000
	v_lshl_add_u64 v[88:89], s[50:51], 0, v[12:13]
	v_lshl_add_u64 v[94:95], s[52:53], 0, v[12:13]
	s_mov_b32 s9, 0
	v_lshlrev_b32_e32 v1, 2, v1
	v_lshlrev_b32_e32 v161, 2, v3
	v_lshl_add_u64 v[98:99], v[10:11], 0, s[0:1]
	s_lshl_b64 s[10:11], s[48:49], 12
	v_lshlrev_b32_e32 v82, 2, v2
	s_mov_b64 s[16:17], 0x1000
	s_movk_i32 s29, 0x1000
	s_mov_b64 s[18:19], 0x1800
	s_mov_b64 s[20:21], 0x10000
	s_mov_b32 s30, 0x10000
	s_mov_b64 s[22:23], 0x10800
	s_brev_b32 s31, 47
	s_mov_b32 s34, 0xf4001000
	s_mov_b32 s35, 0xf4002000
	v_lshlrev_b32_e32 v162, 2, v4
	v_lshlrev_b32_e32 v163, 2, v6
	v_lshlrev_b32_e32 v164, 2, v8
	s_mov_b32 s24, 0x3a000000
	s_mov_b32 s26, 0x358637bd
	s_mov_b32 s36, 0x800000
	s_mov_b32 s37, 0xf0001000
	s_mov_b32 s38, 0xf0002000
	s_branch .LBB0_634

.LBB0_634:
	s_cmpk_lt_i32 s6, 0x2000
	s_cbranch_scc1 .Lr3_noarrive
	s_cmp_lg_u32 s45, 0
	s_cbranch_scc1 .Lr3_noarrive
	s_mov_b32 s45, 1
	s_waitcnt vmcnt(0)
	s_barrier
	s_mov_b64 s[46:47], exec
	v_readlane_b32 s54, v254, 2
	v_readlane_b32 s55, v254, 3
	s_nop 1
	s_and_b64 s[54:55], s[46:47], s[54:55]
	s_mov_b64 exec, s[54:55]
	s_cbranch_execz .Lr3_arrive_join
	s_getreg_b32 s56, hwreg(HW_REG_XCC_ID, 0, 4)
	v_mov_b32_e32 v2, 0x23fc0
	ds_read_b64 v[2:3], v2
	s_lshl_b32 s56, s56, 6
	s_add_u32 s80, s62, 0x409800
	s_addc_u32 s81, s63, 0
	v_mov_b32_e32 v4, s56
	v_mov_b32_e32 v5, 1
	global_atomic_add v6, v4, v5, s[80:81] sc0
	s_waitcnt vmcnt(0) lgkmcnt(0)
	v_add_u32_e32 v6, 1, v6
	v_cmp_eq_u32_e32 vcc, v6, v2
	s_cbranch_vccz .Lr3_arrive_join
	buffer_wbl2 sc1
	s_waitcnt vmcnt(0)
	v_mov_b32_e32 v4, 0x400
	global_atomic_add v4, v5, s[80:81]
.Lr3_arrive_join:
	s_mov_b64 exec, s[46:47]

.LBB0_638:
	s_cmp_gt_u32 s97, 8
	s_cselect_b64 s[0:1], -1, 0
	s_and_b64 s[0:1], s[4:5], s[0:1]
	s_mov_b64 s[50:51], s[96:97]
	s_andn2_b64 vcc, exec, s[0:1]
	s_cbranch_vccnz .LBB0_693
	s_waitcnt vmcnt(0) lgkmcnt(0)
	s_barrier
	s_mov_b64 s[0:1], exec
	v_readlane_b32 s4, v254, 2
	v_readlane_b32 s5, v254, 3
	s_nop 1
	s_and_b64 s[4:5], s[0:1], s[4:5]
	s_mov_b64 exec, s[4:5]
	s_cbranch_execz .Lr3_wait_join
	v_mov_b32_e32 v1, 0x23fc4
	ds_read_b32 v2, v1
	s_add_u32 s6, s62, 0x409800
	s_addc_u32 s7, s63, 0
	v_mov_b32_e32 v1, 0x400
	s_mov_b32 s8, 0
.Lr3_spin:
	global_load_dword v3, v1, s[6:7] sc1
	s_waitcnt vmcnt(0) lgkmcnt(0)
	v_cmp_ge_u32_e32 vcc, v3, v2
	s_cbranch_vccnz .Lr3_spin_done
	s_sleep 1
	s_add_u32 s8, s8, 1
	s_cmp_lt_u32 s8, 0x100000
	s_cbranch_scc1 .Lr3_spin

.Lr3_wait_join:
	s_mov_b64 exec, s[0:1]
	s_barrier
